# no XCD stagger + write-through (sc1) stores for the transposed bf16 weights in P0
# speedup vs baseline: 1.0164x; 1.0042x over previous
; template <int MODE>
; __device__ __forceinline__ void transpose_item(const float* __restrict__ W, int K, int N, bf16_t* __restrict__ WT, LAS float* scr, int item, int lane, const float* __restrict__ ga, const float* __restrict__ gb) {
;     const int nblk = N / 32, kb = item / nblk, nb = item % nblk, k0 = 64 * kb, n0 = 32 * nb;
; #pragma unroll 8
;     for (int i = 0; i < 32; ++i) { const int kk = 2 * i + (lane >> 5); float v = W[(size_t)(k0 + kk) * N + n0 + (lane & 31)];
;         if (MODE == 1) { const int k = k0 + kk; v *= (k < 512) ? ga[k] : gb[k - 512]; }
;         scr[kk * 33 + (lane & 31)] = v; }
.LBB0_77:
	s_lshl_b32 s19, s15, 1
	s_lshl_b32 s20, s13, 1
	v_add_u32_e32 v52, s19, v6
	v_add_u32_e32 v50, s20, v31
	v_add_u32_e32 v54, s20, v33
	v_add_u32_e32 v56, s19, v36
	v_add_u32_e32 v58, s20, v37
	v_add_u32_e32 v60, s19, v38
	v_add_u32_e32 v62, s20, v39
	v_add_u32_e32 v64, s19, v40
	v_add_u32_e32 v66, s20, v41
	v_add_u32_e32 v68, s19, v42
	v_add_u32_e32 v70, s20, v43
	v_add_u32_e32 v72, s19, v44
	v_add_u32_e32 v74, s20, v45
	v_add_u32_e32 v76, s19, v46
	v_add_u32_e32 v78, s20, v47
	v_add_u32_e32 v80, s19, v48
	v_ashrrev_i32_e32 v53, 31, v52
	v_ashrrev_i32_e32 v51, 31, v50
	v_ashrrev_i32_e32 v57, 31, v56
	v_ashrrev_i32_e32 v55, 31, v54
	v_ashrrev_i32_e32 v61, 31, v60
	v_ashrrev_i32_e32 v59, 31, v58
	v_ashrrev_i32_e32 v65, 31, v64
	v_ashrrev_i32_e32 v63, 31, v62
	v_ashrrev_i32_e32 v69, 31, v68
	v_ashrrev_i32_e32 v67, 31, v66
	v_ashrrev_i32_e32 v73, 31, v72
	v_ashrrev_i32_e32 v71, 31, v70
	v_ashrrev_i32_e32 v77, 31, v76
	v_ashrrev_i32_e32 v75, 31, v74
	v_ashrrev_i32_e32 v81, 31, v80
	v_ashrrev_i32_e32 v79, 31, v78
	v_lshlrev_b64 v[52:53], 12, v[52:53]
	v_lshlrev_b64 v[50:51], 12, v[50:51]
	v_lshlrev_b64 v[54:55], 12, v[54:55]
	v_lshlrev_b64 v[56:57], 12, v[56:57]
	v_lshlrev_b64 v[58:59], 12, v[58:59]
	v_lshlrev_b64 v[60:61], 12, v[60:61]
	v_lshlrev_b64 v[62:63], 12, v[62:63]
	v_lshlrev_b64 v[64:65], 12, v[64:65]
	v_lshlrev_b64 v[66:67], 12, v[66:67]
	v_lshlrev_b64 v[68:69], 12, v[68:69]
	v_lshlrev_b64 v[70:71], 12, v[70:71]
	v_lshlrev_b64 v[72:73], 12, v[72:73]
	v_lshlrev_b64 v[74:75], 12, v[74:75]
	v_lshlrev_b64 v[76:77], 12, v[76:77]
	v_lshlrev_b64 v[78:79], 12, v[78:79]
	v_lshlrev_b64 v[80:81], 12, v[80:81]
	v_lshl_add_u64 v[52:53], v[34:35], 0, v[52:53]
	v_lshl_add_u64 v[50:51], v[34:35], 0, v[50:51]
	v_lshl_add_u64 v[56:57], v[34:35], 0, v[56:57]
	v_lshl_add_u64 v[54:55], v[34:35], 0, v[54:55]
	v_lshl_add_u64 v[60:61], v[34:35], 0, v[60:61]
	v_lshl_add_u64 v[58:59], v[34:35], 0, v[58:59]
	v_lshl_add_u64 v[64:65], v[34:35], 0, v[64:65]
	v_lshl_add_u64 v[62:63], v[34:35], 0, v[62:63]
	v_lshl_add_u64 v[68:69], v[34:35], 0, v[68:69]
	v_lshl_add_u64 v[66:67], v[34:35], 0, v[66:67]
	v_lshl_add_u64 v[72:73], v[34:35], 0, v[72:73]
	v_lshl_add_u64 v[70:71], v[34:35], 0, v[70:71]
	v_lshl_add_u64 v[76:77], v[34:35], 0, v[76:77]
	v_lshl_add_u64 v[74:75], v[34:35], 0, v[74:75]
	v_lshl_add_u64 v[80:81], v[34:35], 0, v[80:81]
	v_lshl_add_u64 v[78:79], v[34:35], 0, v[78:79]
	global_load_dword v82, v[52:53], off
	global_load_dword v83, v[50:51], off
	global_load_dword v84, v[56:57], off
	global_load_dword v85, v[54:55], off
	global_load_dword v86, v[60:61], off
	global_load_dword v87, v[58:59], off
	global_load_dword v88, v[64:65], off
	global_load_dword v89, v[62:63], off
	global_load_dword v90, v[68:69], off
	global_load_dword v91, v[66:67], off
	global_load_dword v92, v[72:73], off
	global_load_dword v93, v[70:71], off
	global_load_dword v94, v[76:77], off
	global_load_dword v95, v[74:75], off
	global_load_dword v96, v[80:81], off
	global_load_dword v97, v[78:79], off
	s_add_i32 s15, s15, 16
	s_add_i32 s13, s13, 16
	s_add_i32 s18, s18, -16
	v_add_u32_e32 v50, s19, v2
	v_add_u32_e32 v52, s20, v3
	v_add_u32_e32 v56, s20, v5
	v_add_u32_e32 v54, s19, v20
	v_add_u32_e32 v60, s20, v9
	v_add_u32_e32 v58, s19, v22
	v_add_u32_e32 v64, s20, v21
	v_add_u32_e32 v62, s19, v24
	v_add_u32_e32 v68, s20, v23
	v_add_u32_e32 v66, s19, v26
	v_add_u32_e32 v72, s20, v25
	v_add_u32_e32 v70, s19, v28
	v_add_u32_e32 v76, s20, v27
	v_add_u32_e32 v74, s19, v30
	v_add_u32_e32 v80, s20, v29
	v_add_u32_e32 v78, s19, v32
	s_cmp_lg_u32 s18, 0
	v_mad_u64_u32 v[50:51], s[20:21], v50, s1, v[8:9]
	v_mad_u64_u32 v[52:53], s[20:21], v52, s1, v[8:9]
	v_mad_u64_u32 v[54:55], s[20:21], v54, s1, v[8:9]
	v_mad_u64_u32 v[56:57], s[20:21], v56, s1, v[8:9]
	v_mad_u64_u32 v[58:59], s[20:21], v58, s1, v[8:9]
	v_mad_u64_u32 v[60:61], s[20:21], v60, s1, v[8:9]
	v_mad_u64_u32 v[62:63], s[20:21], v62, s1, v[8:9]
	v_mad_u64_u32 v[64:65], s[20:21], v64, s1, v[8:9]
	v_mad_u64_u32 v[66:67], s[20:21], v66, s1, v[8:9]
	v_mad_u64_u32 v[68:69], s[20:21], v68, s1, v[8:9]
	v_mad_u64_u32 v[70:71], s[20:21], v70, s1, v[8:9]
	v_mad_u64_u32 v[72:73], s[20:21], v72, s1, v[8:9]
	v_mad_u64_u32 v[74:75], s[20:21], v74, s1, v[8:9]
	v_mad_u64_u32 v[76:77], s[20:21], v76, s1, v[8:9]
	v_mad_u64_u32 v[78:79], s[20:21], v78, s1, v[8:9]
	v_mad_u64_u32 v[80:81], s[20:21], v80, s1, v[8:9]
	s_waitcnt vmcnt(15)
	ds_write_b32 v50, v82
	s_waitcnt vmcnt(14)
	ds_write_b32 v52, v83
	s_waitcnt vmcnt(13)
	ds_write_b32 v54, v84
	s_waitcnt vmcnt(12)
	ds_write_b32 v56, v85
	s_waitcnt vmcnt(11)
	ds_write_b32 v58, v86
	s_waitcnt vmcnt(10)
	ds_write_b32 v60, v87
	s_waitcnt vmcnt(9)
	ds_write_b32 v62, v88
	s_waitcnt vmcnt(8)
	ds_write_b32 v64, v89
	s_waitcnt vmcnt(7)
	ds_write_b32 v66, v90
	s_waitcnt vmcnt(6)
	ds_write_b32 v68, v91
	s_waitcnt vmcnt(5)
	ds_write_b32 v70, v92
	s_waitcnt vmcnt(4)
	ds_write_b32 v72, v93
	s_waitcnt vmcnt(3)
	ds_write_b32 v74, v94
	s_waitcnt vmcnt(2)
	ds_write_b32 v76, v95
	s_waitcnt vmcnt(1)
	ds_write_b32 v78, v96
	s_waitcnt vmcnt(0)
	ds_write_b32 v80, v97
	s_cbranch_scc1 .LBB0_77
; #define LAS __attribute__((address_space(3)))
; __device__ __forceinline__ unsigned cvtpk(float lo, float hi) { f32x2 v = {lo, hi}; bf16x2_t b = __builtin_convertvector(v, bf16x2_t); return __builtin_bit_cast(unsigned, b); }
; template <int MODE>
; __device__ __forceinline__ void transpose_item(const float* __restrict__ W, int K, int N, bf16_t* __restrict__ WT, LAS float* scr, int item, int lane, const float* __restrict__ ga, const float* __restrict__ gb) {
;     ...
;     asm volatile("s_waitcnt lgkmcnt(0)" ::: "memory");
;     const int c = lane & 7;
; #pragma unroll
;     for (int j = 0; j < 4; ++j) { const int n = (lane >> 3) + 8 * j; const LAS float* s = scr + (8 * c) * 33 + n;
;         u32x4 o; o.x = cvtpk(s[0 * 33], s[1 * 33]); o.y = cvtpk(s[2 * 33], s[3 * 33]); o.z = cvtpk(s[4 * 33], s[5 * 33]); o.w = cvtpk(s[6 * 33], s[7 * 33]);
;         const int nn = n0 + n; int drow = nn;
;         if (MODE == 2) drow = 256 * (nn >> 7) + (nn & 127);
;         if (MODE == 3) drow = 256 * (nn >> 7) + 128 + (nn & 127);
;         *(u32x4*)(WT + (size_t)drow * K + k0 + 8 * c) = o; }
;     asm volatile("s_waitcnt lgkmcnt(0)" ::: "memory");
	s_waitcnt lgkmcnt(0)
	ds_read2_b32 v[38:39], v110 offset0:33 offset1:41
	ds_read2_b32 v[40:41], v110 offset1:8
	ds_read2_b32 v[42:43], v110 offset0:66 offset1:74
	ds_read2_b32 v[44:45], v110 offset0:99 offset1:107
	ds_read2_b32 v[46:47], v110 offset0:132 offset1:140
	ds_read2_b32 v[50:51], v110 offset0:165 offset1:173
	ds_read2_b32 v[52:53], v110 offset0:198 offset1:206
	ds_read2_b32 v[54:55], v110 offset0:231 offset1:239
	s_and_b32 s14, 0xffff, s14
	s_lshl_b32 s34, s12, 1
	v_lshl_add_u64 v[56:57], v[10:11], 0, s[34:35]
	v_add_u32_e32 v6, s14, v109
	s_waitcnt lgkmcnt(6)
	v_cvt_pk_bf16_f32 v34, v40, v38
	s_waitcnt lgkmcnt(4)
	v_cvt_pk_bf16_f32 v35, v42, v44
	s_waitcnt lgkmcnt(2)
	v_cvt_pk_bf16_f32 v36, v46, v50
	s_waitcnt lgkmcnt(0)
	v_cvt_pk_bf16_f32 v37, v52, v54
	v_mad_i64_i32 v[58:59], s[12:13], v6, s72, v[56:57]
	global_store_dwordx4 v[58:59], v[34:37], off sc1
	v_add_u32_e32 v6, s14, v111
	s_nop 0
	v_cvt_pk_bf16_f32 v34, v41, v39
	v_cvt_pk_bf16_f32 v35, v43, v45
	v_cvt_pk_bf16_f32 v36, v47, v51
	v_cvt_pk_bf16_f32 v37, v53, v55
	ds_read2_b32 v[40:41], v110 offset0:49 offset1:57
	ds_read2_b32 v[42:43], v110 offset0:16 offset1:24
	ds_read2_b32 v[44:45], v110 offset0:82 offset1:90
	ds_read2_b32 v[46:47], v110 offset0:115 offset1:123
	ds_read2_b32 v[50:51], v110 offset0:148 offset1:156
	ds_read2_b32 v[52:53], v110 offset0:181 offset1:189
	ds_read2_b32 v[54:55], v110 offset0:214 offset1:222
	ds_read2_b32 v[58:59], v110 offset0:247 offset1:255
	v_mad_i64_i32 v[38:39], s[12:13], v6, s72, v[56:57]
	v_add_u32_e32 v6, s14, v112
	global_store_dwordx4 v[38:39], v[34:37], off sc1
	v_mad_i64_i32 v[38:39], s[12:13], v6, s72, v[56:57]
	s_waitcnt lgkmcnt(6)
	v_cvt_pk_bf16_f32 v34, v42, v40
	s_waitcnt lgkmcnt(4)
	v_cvt_pk_bf16_f32 v35, v44, v46
	s_waitcnt lgkmcnt(2)
	v_cvt_pk_bf16_f32 v36, v50, v52
	s_waitcnt lgkmcnt(0)
	v_cvt_pk_bf16_f32 v37, v54, v58
	v_add_u32_e32 v6, s14, v113
	global_store_dwordx4 v[38:39], v[34:37], off sc1
	v_mad_i64_i32 v[38:39], s[12:13], v6, s72, v[56:57]
	s_nop 0
	v_cvt_pk_bf16_f32 v34, v43, v41
	v_cvt_pk_bf16_f32 v35, v45, v47
	v_cvt_pk_bf16_f32 v36, v51, v53
	v_cvt_pk_bf16_f32 v37, v55, v59
	global_store_dwordx4 v[38:39], v[34:37], off sc1
	s_waitcnt lgkmcnt(0)

; template <int MODE>
; __device__ __forceinline__ void transpose_item(const float* __restrict__ W, int K, int N, bf16_t* __restrict__ WT, LAS float* scr, int item, int lane, const float* __restrict__ ga, const float* __restrict__ gb) {
;     const int nblk = N / 32, kb = item / nblk, nb = item % nblk, k0 = 64 * kb, n0 = 32 * nb;
; #pragma unroll 8
;     for (int i = 0; i < 32; ++i) { const int kk = 2 * i + (lane >> 5); float v = W[(size_t)(k0 + kk) * N + n0 + (lane & 31)];
;         if (MODE == 1) { const int k = k0 + kk; v *= (k < 512) ? ga[k] : gb[k - 512]; }
;         scr[kk * 33 + (lane & 31)] = v; }
.LBB0_82:
	s_lshl_b32 s19, s15, 1
	s_lshl_b32 s34, s14, 1
	v_add_u32_e32 v50, s19, v6
	v_add_u32_e32 v52, s34, v31
	v_add_u32_e32 v56, s34, v33
	v_add_u32_e32 v54, s19, v36
	v_add_u32_e32 v60, s34, v37
	v_add_u32_e32 v58, s19, v38
	v_add_u32_e32 v64, s34, v39
	v_add_u32_e32 v62, s19, v40
	v_add_u32_e32 v68, s34, v41
	v_add_u32_e32 v66, s19, v42
	v_add_u32_e32 v72, s34, v43
	v_add_u32_e32 v70, s19, v44
	v_add_u32_e32 v76, s34, v45
	v_add_u32_e32 v74, s19, v46
	v_add_u32_e32 v80, s34, v47
	v_add_u32_e32 v78, s19, v48
	v_mad_i64_i32 v[50:51], s[20:21], v50, s73, v[34:35]
	v_mad_i64_i32 v[52:53], s[20:21], v52, s73, v[34:35]
	v_mad_i64_i32 v[54:55], s[20:21], v54, s73, v[34:35]
	v_mad_i64_i32 v[56:57], s[20:21], v56, s73, v[34:35]
	v_mad_i64_i32 v[58:59], s[20:21], v58, s73, v[34:35]
	v_mad_i64_i32 v[60:61], s[20:21], v60, s73, v[34:35]
	v_mad_i64_i32 v[62:63], s[20:21], v62, s73, v[34:35]
	v_mad_i64_i32 v[64:65], s[20:21], v64, s73, v[34:35]
	v_mad_i64_i32 v[66:67], s[20:21], v66, s73, v[34:35]
	v_mad_i64_i32 v[68:69], s[20:21], v68, s73, v[34:35]
	v_mad_i64_i32 v[70:71], s[20:21], v70, s73, v[34:35]
	v_mad_i64_i32 v[72:73], s[20:21], v72, s73, v[34:35]
	v_mad_i64_i32 v[74:75], s[20:21], v74, s73, v[34:35]
	v_mad_i64_i32 v[76:77], s[20:21], v76, s73, v[34:35]
	v_mad_i64_i32 v[78:79], s[20:21], v78, s73, v[34:35]
	v_mad_i64_i32 v[80:81], s[20:21], v80, s73, v[34:35]
	global_load_dword v82, v[50:51], off
	global_load_dword v83, v[52:53], off
	global_load_dword v84, v[54:55], off
	global_load_dword v85, v[56:57], off
	global_load_dword v86, v[58:59], off
	global_load_dword v87, v[60:61], off
	global_load_dword v88, v[62:63], off
	global_load_dword v89, v[64:65], off
	global_load_dword v90, v[66:67], off
	global_load_dword v91, v[68:69], off
	global_load_dword v92, v[70:71], off
	global_load_dword v93, v[72:73], off
	global_load_dword v94, v[74:75], off
	global_load_dword v95, v[76:77], off
	global_load_dword v96, v[78:79], off
	global_load_dword v97, v[80:81], off
	s_add_i32 s15, s15, 16
	s_add_i32 s14, s14, 16
	s_add_i32 s18, s18, -16
	v_add_u32_e32 v50, s19, v2
	v_add_u32_e32 v52, s34, v3
	v_add_u32_e32 v56, s34, v5
	v_add_u32_e32 v54, s19, v20
	v_add_u32_e32 v60, s34, v9
	v_add_u32_e32 v58, s19, v22
	v_add_u32_e32 v64, s34, v21
	v_add_u32_e32 v62, s19, v24
	v_add_u32_e32 v68, s34, v23
	v_add_u32_e32 v66, s19, v26
	v_add_u32_e32 v72, s34, v25
	v_add_u32_e32 v70, s19, v28
	v_add_u32_e32 v76, s34, v27
	v_add_u32_e32 v74, s19, v30
	v_add_u32_e32 v80, s34, v29
	v_add_u32_e32 v78, s19, v32
	s_cmp_lg_u32 s18, 0
	v_mad_u64_u32 v[50:51], s[20:21], v50, s1, v[8:9]
	v_mad_u64_u32 v[52:53], s[20:21], v52, s1, v[8:9]
	v_mad_u64_u32 v[54:55], s[20:21], v54, s1, v[8:9]
	v_mad_u64_u32 v[56:57], s[20:21], v56, s1, v[8:9]
	v_mad_u64_u32 v[58:59], s[20:21], v58, s1, v[8:9]
	v_mad_u64_u32 v[60:61], s[20:21], v60, s1, v[8:9]
	v_mad_u64_u32 v[62:63], s[20:21], v62, s1, v[8:9]
	v_mad_u64_u32 v[64:65], s[20:21], v64, s1, v[8:9]
	v_mad_u64_u32 v[66:67], s[20:21], v66, s1, v[8:9]
	v_mad_u64_u32 v[68:69], s[20:21], v68, s1, v[8:9]
	v_mad_u64_u32 v[70:71], s[20:21], v70, s1, v[8:9]
	v_mad_u64_u32 v[72:73], s[20:21], v72, s1, v[8:9]
	v_mad_u64_u32 v[74:75], s[20:21], v74, s1, v[8:9]
	v_mad_u64_u32 v[76:77], s[20:21], v76, s1, v[8:9]
	v_mad_u64_u32 v[78:79], s[20:21], v78, s1, v[8:9]
	v_mad_u64_u32 v[80:81], s[20:21], v80, s1, v[8:9]
	s_waitcnt vmcnt(15)
	ds_write_b32 v50, v82
	s_waitcnt vmcnt(14)
	ds_write_b32 v52, v83
	s_waitcnt vmcnt(13)
	ds_write_b32 v54, v84
	s_waitcnt vmcnt(12)
	ds_write_b32 v56, v85
	s_waitcnt vmcnt(11)
	ds_write_b32 v58, v86
	s_waitcnt vmcnt(10)
	ds_write_b32 v60, v87
	s_waitcnt vmcnt(9)
	ds_write_b32 v62, v88
	s_waitcnt vmcnt(8)
	ds_write_b32 v64, v89
	s_waitcnt vmcnt(7)
	ds_write_b32 v66, v90
	s_waitcnt vmcnt(6)
	ds_write_b32 v68, v91
	s_waitcnt vmcnt(5)
	ds_write_b32 v70, v92
	s_waitcnt vmcnt(4)
	ds_write_b32 v72, v93
	s_waitcnt vmcnt(3)
	ds_write_b32 v74, v94
	s_waitcnt vmcnt(2)
	ds_write_b32 v76, v95
	s_waitcnt vmcnt(1)
	ds_write_b32 v78, v96
	s_waitcnt vmcnt(0)
	ds_write_b32 v80, v97
	s_cbranch_scc1 .LBB0_82
; #define LAS __attribute__((address_space(3)))
; __device__ __forceinline__ unsigned cvtpk(float lo, float hi) { f32x2 v = {lo, hi}; bf16x2_t b = __builtin_convertvector(v, bf16x2_t); return __builtin_bit_cast(unsigned, b); }
; template <int MODE>
; __device__ __forceinline__ void transpose_item(const float* __restrict__ W, int K, int N, bf16_t* __restrict__ WT, LAS float* scr, int item, int lane, const float* __restrict__ ga, const float* __restrict__ gb) {
;     ...
;     asm volatile("s_waitcnt lgkmcnt(0)" ::: "memory");
;     const int c = lane & 7;
; #pragma unroll
;     for (int j = 0; j < 4; ++j) { const int n = (lane >> 3) + 8 * j; const LAS float* s = scr + (8 * c) * 33 + n;
;         u32x4 o; o.x = cvtpk(s[0 * 33], s[1 * 33]); o.y = cvtpk(s[2 * 33], s[3 * 33]); o.z = cvtpk(s[4 * 33], s[5 * 33]); o.w = cvtpk(s[6 * 33], s[7 * 33]);
;         const int nn = n0 + n; int drow = nn;
;         if (MODE == 2) drow = 256 * (nn >> 7) + (nn & 127);
;         if (MODE == 3) drow = 256 * (nn >> 7) + 128 + (nn & 127);
;         *(u32x4*)(WT + (size_t)drow * K + k0 + 8 * c) = o; }
;     asm volatile("s_waitcnt lgkmcnt(0)" ::: "memory");
	s_and_b32 s13, 0xffff, s13
	s_waitcnt lgkmcnt(0)
	v_add_u32_e32 v6, s13, v109
	ds_read2_b32 v[38:39], v110 offset0:33 offset1:41
	ds_read2_b32 v[40:41], v110 offset1:8
	ds_read2_b32 v[42:43], v110 offset0:66 offset1:74
	ds_read2_b32 v[44:45], v110 offset0:99 offset1:107
	ds_read2_b32 v[46:47], v110 offset0:132 offset1:140
	ds_read2_b32 v[50:51], v110 offset0:165 offset1:173
	ds_read2_b32 v[52:53], v110 offset0:198 offset1:206
	ds_read2_b32 v[54:55], v110 offset0:231 offset1:239
	v_lshlrev_b32_e32 v31, 1, v6
	v_and_b32_e32 v31, 0xffffff00, v31
	v_and_b32_e32 v6, 0x7f, v6
	s_and_b32 s12, 0xffff, s12
	v_or3_b32 v58, v6, v31, s71
	v_add_u32_e32 v6, s13, v111
	s_lshl_b32 s34, s12, 1
	v_ashrrev_i32_e32 v59, 31, v58
	v_lshlrev_b32_e32 v31, 1, v6
	v_lshl_add_u64 v[56:57], v[12:13], 0, s[34:35]
	v_lshlrev_b64 v[58:59], 11, v[58:59]
	v_and_b32_e32 v31, 0xffffff00, v31
	v_and_b32_e32 v6, 0x7f, v6
	s_waitcnt lgkmcnt(6)
	v_cvt_pk_bf16_f32 v34, v40, v38
	s_waitcnt lgkmcnt(4)
	v_cvt_pk_bf16_f32 v35, v42, v44
	s_waitcnt lgkmcnt(2)
	v_cvt_pk_bf16_f32 v36, v46, v50
	s_waitcnt lgkmcnt(0)
	v_cvt_pk_bf16_f32 v37, v52, v54
	v_lshl_add_u64 v[58:59], v[56:57], 0, v[58:59]
	v_or3_b32 v38, v6, v31, s71
	global_store_dwordx4 v[58:59], v[34:37], off sc1
	v_add_u32_e32 v6, s13, v112
	v_lshlrev_b32_e32 v31, 1, v6
	v_cvt_pk_bf16_f32 v34, v41, v39
	v_ashrrev_i32_e32 v39, 31, v38
	v_cvt_pk_bf16_f32 v35, v43, v45
	v_cvt_pk_bf16_f32 v36, v47, v51
	v_cvt_pk_bf16_f32 v37, v53, v55
	v_lshlrev_b64 v[38:39], 11, v[38:39]
	ds_read2_b32 v[40:41], v110 offset0:16 offset1:24
	ds_read2_b32 v[42:43], v110 offset0:49 offset1:57
	ds_read2_b32 v[44:45], v110 offset0:82 offset1:90
	ds_read2_b32 v[46:47], v110 offset0:115 offset1:123
	ds_read2_b32 v[50:51], v110 offset0:148 offset1:156
	ds_read2_b32 v[52:53], v110 offset0:181 offset1:189
	ds_read2_b32 v[54:55], v110 offset0:214 offset1:222
	ds_read2_b32 v[58:59], v110 offset0:247 offset1:255
	v_lshl_add_u64 v[38:39], v[56:57], 0, v[38:39]
	v_and_b32_e32 v31, 0xffffff00, v31
	v_and_b32_e32 v6, 0x7f, v6
	global_store_dwordx4 v[38:39], v[34:37], off sc1
	v_or3_b32 v38, v6, v31, s71
	v_ashrrev_i32_e32 v39, 31, v38
	v_add_u32_e32 v6, s13, v113
	v_lshlrev_b64 v[38:39], 11, v[38:39]
	v_lshlrev_b32_e32 v31, 1, v6
	s_waitcnt lgkmcnt(6)
	v_cvt_pk_bf16_f32 v34, v40, v42
	s_waitcnt lgkmcnt(4)
	v_cvt_pk_bf16_f32 v35, v44, v46
	s_waitcnt lgkmcnt(2)
	v_cvt_pk_bf16_f32 v36, v50, v52
	s_waitcnt lgkmcnt(0)
	v_cvt_pk_bf16_f32 v37, v54, v58
	v_lshl_add_u64 v[38:39], v[56:57], 0, v[38:39]
	v_and_b32_e32 v31, 0xffffff00, v31
	v_and_b32_e32 v6, 0x7f, v6
	global_store_dwordx4 v[38:39], v[34:37], off sc1
	v_or3_b32 v38, v6, v31, s71
	v_ashrrev_i32_e32 v39, 31, v38
	v_lshlrev_b64 v[38:39], 11, v[38:39]
	v_cvt_pk_bf16_f32 v34, v41, v43
	v_cvt_pk_bf16_f32 v35, v45, v47
	v_cvt_pk_bf16_f32 v36, v51, v53
	v_cvt_pk_bf16_f32 v37, v55, v59
	v_lshl_add_u64 v[38:39], v[56:57], 0, v[38:39]
	global_store_dwordx4 v[38:39], v[34:37], off sc1
	s_waitcnt lgkmcnt(0)

; #define LAS __attribute__((address_space(3)))
; __device__ __forceinline__ unsigned cvtpk(float lo, float hi) { f32x2 v = {lo, hi}; bf16x2_t b = __builtin_convertvector(v, bf16x2_t); return __builtin_bit_cast(unsigned, b); }
; template <int MODE>
; __device__ __forceinline__ void transpose_item(const float* __restrict__ W, int K, int N, bf16_t* __restrict__ WT, LAS float* scr, int item, int lane, const float* __restrict__ ga, const float* __restrict__ gb) {
;     const int nblk = N / 32, kb = item / nblk, nb = item % nblk, k0 = 64 * kb, n0 = 32 * nb;
; #pragma unroll 8
;     for (int i = 0; i < 32; ++i) { const int kk = 2 * i + (lane >> 5); float v = W[(size_t)(k0 + kk) * N + n0 + (lane & 31)];
;         if (MODE == 1) { const int k = k0 + kk; v *= (k < 512) ? ga[k] : gb[k - 512]; }
;         scr[kk * 33 + (lane & 31)] = v; }
;     asm volatile("s_waitcnt lgkmcnt(0)" ::: "memory");
;     const int c = lane & 7;
; #pragma unroll
;     for (int j = 0; j < 4; ++j) { const int n = (lane >> 3) + 8 * j; const LAS float* s = scr + (8 * c) * 33 + n;
;         u32x4 o; o.x = cvtpk(s[0 * 33], s[1 * 33]); o.y = cvtpk(s[2 * 33], s[3 * 33]); o.z = cvtpk(s[4 * 33], s[5 * 33]); o.w = cvtpk(s[6 * 33], s[7 * 33]);
;         const int nn = n0 + n; int drow = nn;
;         if (MODE == 2) drow = 256 * (nn >> 7) + (nn & 127);
;         if (MODE == 3) drow = 256 * (nn >> 7) + 128 + (nn & 127);
;         *(u32x4*)(WT + (size_t)drow * K + k0 + 8 * c) = o; }
;     asm volatile("s_waitcnt lgkmcnt(0)" ::: "memory");
.LBB0_87:
	s_lshl_b32 s19, s15, 1
	s_lshl_b32 s34, s14, 1
	v_add_u32_e32 v50, s19, v6
	v_add_u32_e32 v52, s34, v31
	v_add_u32_e32 v56, s34, v33
	v_add_u32_e32 v54, s19, v36
	v_add_u32_e32 v60, s34, v37
	v_add_u32_e32 v58, s19, v38
	v_add_u32_e32 v64, s34, v39
	v_add_u32_e32 v62, s19, v40
	v_add_u32_e32 v68, s34, v41
	v_add_u32_e32 v66, s19, v42
	v_add_u32_e32 v72, s34, v43
	v_add_u32_e32 v70, s19, v44
	v_add_u32_e32 v76, s34, v45
	v_add_u32_e32 v74, s19, v46
	v_add_u32_e32 v80, s34, v47
	v_add_u32_e32 v78, s19, v48
	v_mad_i64_i32 v[50:51], s[20:21], v50, s73, v[34:35]
	v_mad_i64_i32 v[52:53], s[20:21], v52, s73, v[34:35]
	v_mad_i64_i32 v[54:55], s[20:21], v54, s73, v[34:35]
	v_mad_i64_i32 v[56:57], s[20:21], v56, s73, v[34:35]
	v_mad_i64_i32 v[58:59], s[20:21], v58, s73, v[34:35]
	v_mad_i64_i32 v[60:61], s[20:21], v60, s73, v[34:35]
	v_mad_i64_i32 v[62:63], s[20:21], v62, s73, v[34:35]
	v_mad_i64_i32 v[64:65], s[20:21], v64, s73, v[34:35]
	v_mad_i64_i32 v[66:67], s[20:21], v66, s73, v[34:35]
	v_mad_i64_i32 v[68:69], s[20:21], v68, s73, v[34:35]
	v_mad_i64_i32 v[70:71], s[20:21], v70, s73, v[34:35]
	v_mad_i64_i32 v[72:73], s[20:21], v72, s73, v[34:35]
	v_mad_i64_i32 v[74:75], s[20:21], v74, s73, v[34:35]
	v_mad_i64_i32 v[76:77], s[20:21], v76, s73, v[34:35]
	v_mad_i64_i32 v[78:79], s[20:21], v78, s73, v[34:35]
	v_mad_i64_i32 v[80:81], s[20:21], v80, s73, v[34:35]
	global_load_dword v82, v[50:51], off
	global_load_dword v83, v[52:53], off
	global_load_dword v84, v[54:55], off
	global_load_dword v85, v[56:57], off
	global_load_dword v86, v[58:59], off
	global_load_dword v87, v[60:61], off
	global_load_dword v88, v[62:63], off
	global_load_dword v89, v[64:65], off
	global_load_dword v90, v[66:67], off
	global_load_dword v91, v[68:69], off
	global_load_dword v92, v[70:71], off
	global_load_dword v93, v[72:73], off
	global_load_dword v94, v[74:75], off
	global_load_dword v95, v[76:77], off
	global_load_dword v96, v[78:79], off
	global_load_dword v97, v[80:81], off
	s_add_i32 s15, s15, 16
	s_add_i32 s14, s14, 16
	s_add_i32 s18, s18, -16
	v_add_u32_e32 v50, s19, v2
	v_add_u32_e32 v52, s34, v3
	v_add_u32_e32 v56, s34, v5
	v_add_u32_e32 v54, s19, v20
	v_add_u32_e32 v60, s34, v9
	v_add_u32_e32 v58, s19, v22
	v_add_u32_e32 v64, s34, v21
	v_add_u32_e32 v62, s19, v24
	v_add_u32_e32 v68, s34, v23
	v_add_u32_e32 v66, s19, v26
	v_add_u32_e32 v72, s34, v25
	v_add_u32_e32 v70, s19, v28
	v_add_u32_e32 v76, s34, v27
	v_add_u32_e32 v74, s19, v30
	v_add_u32_e32 v80, s34, v29
	v_add_u32_e32 v78, s19, v32
	s_cmp_lg_u32 s18, 0
	v_mad_u64_u32 v[50:51], s[20:21], v50, s1, v[8:9]
	v_mad_u64_u32 v[52:53], s[20:21], v52, s1, v[8:9]
	v_mad_u64_u32 v[54:55], s[20:21], v54, s1, v[8:9]
	v_mad_u64_u32 v[56:57], s[20:21], v56, s1, v[8:9]
	v_mad_u64_u32 v[58:59], s[20:21], v58, s1, v[8:9]
	v_mad_u64_u32 v[60:61], s[20:21], v60, s1, v[8:9]
	v_mad_u64_u32 v[62:63], s[20:21], v62, s1, v[8:9]
	v_mad_u64_u32 v[64:65], s[20:21], v64, s1, v[8:9]
	v_mad_u64_u32 v[66:67], s[20:21], v66, s1, v[8:9]
	v_mad_u64_u32 v[68:69], s[20:21], v68, s1, v[8:9]
	v_mad_u64_u32 v[70:71], s[20:21], v70, s1, v[8:9]
	v_mad_u64_u32 v[72:73], s[20:21], v72, s1, v[8:9]
	v_mad_u64_u32 v[74:75], s[20:21], v74, s1, v[8:9]
	v_mad_u64_u32 v[76:77], s[20:21], v76, s1, v[8:9]
	v_mad_u64_u32 v[78:79], s[20:21], v78, s1, v[8:9]
	v_mad_u64_u32 v[80:81], s[20:21], v80, s1, v[8:9]
	s_waitcnt vmcnt(15)
	ds_write_b32 v50, v82
	s_waitcnt vmcnt(14)
	ds_write_b32 v52, v83
	s_waitcnt vmcnt(13)
	ds_write_b32 v54, v84
	s_waitcnt vmcnt(12)
	ds_write_b32 v56, v85
	s_waitcnt vmcnt(11)
	ds_write_b32 v58, v86
	s_waitcnt vmcnt(10)
	ds_write_b32 v60, v87
	s_waitcnt vmcnt(9)
	ds_write_b32 v62, v88
	s_waitcnt vmcnt(8)
	ds_write_b32 v64, v89
	s_waitcnt vmcnt(7)
	ds_write_b32 v66, v90
	s_waitcnt vmcnt(6)
	ds_write_b32 v68, v91
	s_waitcnt vmcnt(5)
	ds_write_b32 v70, v92
	s_waitcnt vmcnt(4)
	ds_write_b32 v72, v93
	s_waitcnt vmcnt(3)
	ds_write_b32 v74, v94
	s_waitcnt vmcnt(2)
	ds_write_b32 v76, v95
	s_waitcnt vmcnt(1)
	ds_write_b32 v78, v96
	s_waitcnt vmcnt(0)
	ds_write_b32 v80, v97
	s_cbranch_scc1 .LBB0_87
	s_and_b32 s13, 0xffff, s13
	s_waitcnt lgkmcnt(0)
	ds_read2_b32 v[38:39], v110 offset0:33 offset1:41
	ds_read2_b32 v[40:41], v110 offset1:8
	ds_read2_b32 v[42:43], v110 offset0:66 offset1:74
	ds_read2_b32 v[44:45], v110 offset0:99 offset1:107
	ds_read2_b32 v[46:47], v110 offset0:132 offset1:140
	ds_read2_b32 v[50:51], v110 offset0:165 offset1:173
	ds_read2_b32 v[52:53], v110 offset0:198 offset1:206
	ds_read2_b32 v[54:55], v110 offset0:231 offset1:239
	v_add_u32_e32 v6, s13, v109
	v_lshlrev_b32_e32 v31, 1, v6
	v_and_b32_e32 v6, 0x7f, v6
	s_and_b32 s12, 0xffff, s12
	v_and_or_b32 v58, v31, s74, v6
	s_lshl_b32 s34, s12, 1
	v_ashrrev_i32_e32 v59, 31, v58
	v_add_u32_e32 v6, s13, v111
	v_lshl_add_u64 v[56:57], v[12:13], 0, s[34:35]
	v_lshlrev_b64 v[58:59], 11, v[58:59]
	v_lshlrev_b32_e32 v31, 1, v6
	v_and_b32_e32 v6, 0x7f, v6
	s_waitcnt lgkmcnt(6)
	v_cvt_pk_bf16_f32 v34, v40, v38
	s_waitcnt lgkmcnt(4)
	v_cvt_pk_bf16_f32 v35, v42, v44
	s_waitcnt lgkmcnt(2)
	v_cvt_pk_bf16_f32 v36, v46, v50
	s_waitcnt lgkmcnt(0)
	v_cvt_pk_bf16_f32 v37, v52, v54
	v_lshl_add_u64 v[58:59], v[56:57], 0, v[58:59]
	v_and_or_b32 v38, v31, s74, v6
	global_store_dwordx4 v[58:59], v[34:37], off sc1
	v_add_u32_e32 v6, s13, v112
	v_lshlrev_b32_e32 v31, 1, v6
	v_cvt_pk_bf16_f32 v34, v41, v39
	v_ashrrev_i32_e32 v39, 31, v38
	v_cvt_pk_bf16_f32 v35, v43, v45
	v_cvt_pk_bf16_f32 v36, v47, v51
	v_cvt_pk_bf16_f32 v37, v53, v55
	v_lshlrev_b64 v[38:39], 11, v[38:39]
	ds_read2_b32 v[40:41], v110 offset0:16 offset1:24
	ds_read2_b32 v[42:43], v110 offset0:49 offset1:57
	ds_read2_b32 v[44:45], v110 offset0:82 offset1:90
	ds_read2_b32 v[46:47], v110 offset0:115 offset1:123
	ds_read2_b32 v[50:51], v110 offset0:148 offset1:156
	ds_read2_b32 v[52:53], v110 offset0:181 offset1:189
	ds_read2_b32 v[54:55], v110 offset0:214 offset1:222
	ds_read2_b32 v[58:59], v110 offset0:247 offset1:255
	v_lshl_add_u64 v[38:39], v[56:57], 0, v[38:39]
	v_and_b32_e32 v6, 0x7f, v6
	global_store_dwordx4 v[38:39], v[34:37], off sc1
	v_and_or_b32 v38, v31, s74, v6
	v_ashrrev_i32_e32 v39, 31, v38
	v_lshlrev_b64 v[38:39], 11, v[38:39]
	v_add_u32_e32 v6, s13, v113
	s_waitcnt lgkmcnt(6)
	v_cvt_pk_bf16_f32 v34, v40, v42
	s_waitcnt lgkmcnt(4)
	v_cvt_pk_bf16_f32 v35, v44, v46
	s_waitcnt lgkmcnt(2)
	v_cvt_pk_bf16_f32 v36, v50, v52
	s_waitcnt lgkmcnt(0)
	v_cvt_pk_bf16_f32 v37, v54, v58
	v_lshl_add_u64 v[38:39], v[56:57], 0, v[38:39]
	v_lshlrev_b32_e32 v31, 1, v6
	v_and_b32_e32 v6, 0x7f, v6
	global_store_dwordx4 v[38:39], v[34:37], off sc1
	v_and_or_b32 v38, v31, s74, v6
	v_ashrrev_i32_e32 v39, 31, v38
	v_lshlrev_b64 v[38:39], 11, v[38:39]
	v_cvt_pk_bf16_f32 v34, v41, v43
	v_cvt_pk_bf16_f32 v35, v45, v47
	v_cvt_pk_bf16_f32 v36, v51, v53
	v_cvt_pk_bf16_f32 v37, v55, v59
	v_lshl_add_u64 v[38:39], v[56:57], 0, v[38:39]
	global_store_dwordx4 v[38:39], v[34:37], off sc1
	s_waitcnt lgkmcnt(0)

; template <int MODE>
; __device__ __forceinline__ void transpose_item(const float* __restrict__ W, int K, int N, bf16_t* __restrict__ WT, LAS float* scr, int item, int lane, const float* __restrict__ ga, const float* __restrict__ gb) {
;     ...
;     for (int i = 0; i < 32; ++i) { const int kk = 2 * i + (lane >> 5); float v = W[(size_t)(k0 + kk) * N + n0 + (lane & 31)];
;         if (MODE == 1) { const int k = k0 + kk; v *= (k < 512) ? ga[k] : gb[k - 512]; }
;         scr[kk * 33 + (lane & 31)] = v; }
.LBB0_92:
	s_lshl_b32 s92, s61, 1
	v_add_u32_e32 v86, s92, v31
	s_lshl_b32 s91, s62, 1
	v_ashrrev_i32_e32 v87, 31, v86
	v_add_u32_e32 v84, s91, v6
	v_lshlrev_b64 v[50:51], 2, v[86:87]
	v_ashrrev_i32_e32 v85, 31, v84
	v_lshl_add_u64 v[102:103], s[18:19], 0, v[50:51]
	v_lshl_add_u64 v[50:51], s[20:21], 0, v[50:51]
	v_add_u32_e32 v78, s92, v33
	v_lshlrev_b64 v[52:53], 2, v[84:85]
	v_lshl_add_u64 v[50:51], v[50:51], 0, s[58:59]
	v_cmp_gt_i32_e32 vcc, s75, v86
	v_ashrrev_i32_e32 v79, 31, v78
	v_add_u32_e32 v76, s91, v36
	v_cndmask_b32_e32 v51, v51, v103, vcc
	v_cndmask_b32_e32 v50, v50, v102, vcc
	v_lshl_add_u64 v[102:103], s[18:19], 0, v[52:53]
	v_lshl_add_u64 v[52:53], s[20:21], 0, v[52:53]
	v_lshlrev_b64 v[54:55], 2, v[78:79]
	v_lshl_add_u64 v[52:53], v[52:53], 0, s[58:59]
	v_cmp_gt_i32_e32 vcc, s75, v84
	v_ashrrev_i32_e32 v77, 31, v76
	v_add_u32_e32 v82, s92, v37
	v_cndmask_b32_e32 v53, v53, v103, vcc
	v_cndmask_b32_e32 v52, v52, v102, vcc
	v_lshl_add_u64 v[102:103], s[18:19], 0, v[54:55]
	v_lshl_add_u64 v[54:55], s[20:21], 0, v[54:55]
	v_lshlrev_b64 v[56:57], 2, v[76:77]
	v_lshl_add_u64 v[54:55], v[54:55], 0, s[58:59]
	v_cmp_gt_i32_e32 vcc, s75, v78
	v_ashrrev_i32_e32 v83, 31, v82
	v_add_u32_e32 v80, s91, v38
	v_cndmask_b32_e32 v55, v55, v103, vcc
	v_cndmask_b32_e32 v54, v54, v102, vcc
	v_lshl_add_u64 v[102:103], s[18:19], 0, v[56:57]
	v_lshl_add_u64 v[56:57], s[20:21], 0, v[56:57]
	v_lshlrev_b64 v[58:59], 2, v[82:83]
	v_lshl_add_u64 v[56:57], v[56:57], 0, s[58:59]
	v_cmp_gt_i32_e32 vcc, s75, v76
	v_ashrrev_i32_e32 v81, 31, v80
	v_add_u32_e32 v90, s92, v39
	v_cndmask_b32_e32 v57, v57, v103, vcc
	v_cndmask_b32_e32 v56, v56, v102, vcc
	v_lshl_add_u64 v[102:103], s[18:19], 0, v[58:59]
	v_lshl_add_u64 v[58:59], s[20:21], 0, v[58:59]
	v_lshlrev_b64 v[60:61], 2, v[80:81]
	v_lshl_add_u64 v[58:59], v[58:59], 0, s[58:59]
	v_cmp_gt_i32_e32 vcc, s75, v82
	v_ashrrev_i32_e32 v91, 31, v90
	v_add_u32_e32 v88, s91, v40
	v_cndmask_b32_e32 v59, v59, v103, vcc
	v_cndmask_b32_e32 v58, v58, v102, vcc
	v_lshl_add_u64 v[102:103], s[18:19], 0, v[60:61]
	v_lshl_add_u64 v[60:61], s[20:21], 0, v[60:61]
	v_lshlrev_b64 v[62:63], 2, v[90:91]
	v_lshl_add_u64 v[60:61], v[60:61], 0, s[58:59]
	v_cmp_gt_i32_e32 vcc, s75, v80
	v_ashrrev_i32_e32 v89, 31, v88
	v_add_u32_e32 v94, s92, v41
	v_cndmask_b32_e32 v61, v61, v103, vcc
	v_cndmask_b32_e32 v60, v60, v102, vcc
	v_lshl_add_u64 v[102:103], s[18:19], 0, v[62:63]
	v_lshl_add_u64 v[62:63], s[20:21], 0, v[62:63]
	v_lshlrev_b64 v[64:65], 2, v[88:89]
	v_lshl_add_u64 v[62:63], v[62:63], 0, s[58:59]
	v_cmp_gt_i32_e32 vcc, s75, v90
	v_ashrrev_i32_e32 v95, 31, v94
	v_add_u32_e32 v92, s91, v42
	v_cndmask_b32_e32 v63, v63, v103, vcc
	v_cndmask_b32_e32 v62, v62, v102, vcc
	v_lshl_add_u64 v[102:103], s[18:19], 0, v[64:65]
	v_lshl_add_u64 v[64:65], s[20:21], 0, v[64:65]
	v_lshlrev_b64 v[66:67], 2, v[94:95]
	v_lshl_add_u64 v[64:65], v[64:65], 0, s[58:59]
	v_cmp_gt_i32_e32 vcc, s75, v88
	v_ashrrev_i32_e32 v93, 31, v92
	v_add_u32_e32 v98, s92, v43
	v_cndmask_b32_e32 v65, v65, v103, vcc
	v_cndmask_b32_e32 v64, v64, v102, vcc
	v_lshl_add_u64 v[102:103], s[18:19], 0, v[66:67]
	v_lshl_add_u64 v[66:67], s[20:21], 0, v[66:67]
	v_lshlrev_b64 v[68:69], 2, v[92:93]
	v_lshl_add_u64 v[66:67], v[66:67], 0, s[58:59]
	v_cmp_gt_i32_e32 vcc, s75, v94
	v_ashrrev_i32_e32 v99, 31, v98
	v_add_u32_e32 v96, s91, v44
	v_cndmask_b32_e32 v67, v67, v103, vcc
	v_cndmask_b32_e32 v66, v66, v102, vcc
	v_lshl_add_u64 v[102:103], s[18:19], 0, v[68:69]
	v_lshl_add_u64 v[68:69], s[20:21], 0, v[68:69]
	v_lshlrev_b64 v[70:71], 2, v[98:99]
	v_lshl_add_u64 v[68:69], v[68:69], 0, s[58:59]
	v_cmp_gt_i32_e32 vcc, s75, v92
	v_ashrrev_i32_e32 v97, 31, v96
	v_add_u32_e32 v100, s92, v45
	v_cndmask_b32_e32 v69, v69, v103, vcc
	v_cndmask_b32_e32 v68, v68, v102, vcc
	v_lshl_add_u64 v[102:103], s[18:19], 0, v[70:71]
	v_lshl_add_u64 v[70:71], s[20:21], 0, v[70:71]
	v_lshlrev_b64 v[72:73], 2, v[96:97]
	v_lshl_add_u64 v[70:71], v[70:71], 0, s[58:59]
	v_cmp_gt_i32_e32 vcc, s75, v98
	v_ashrrev_i32_e32 v101, 31, v100
	v_lshlrev_b64 v[74:75], 2, v[100:101]
	v_cndmask_b32_e32 v71, v71, v103, vcc
	v_cndmask_b32_e32 v70, v70, v102, vcc
	v_lshl_add_u64 v[102:103], s[18:19], 0, v[72:73]
	v_lshl_add_u64 v[72:73], s[20:21], 0, v[72:73]
	v_lshl_add_u64 v[72:73], v[72:73], 0, s[58:59]
	v_cmp_gt_i32_e32 vcc, s75, v96
	v_lshlrev_b64 v[86:87], 12, v[86:87]
	v_lshlrev_b64 v[84:85], 12, v[84:85]
	v_lshlrev_b64 v[78:79], 12, v[78:79]
	v_lshlrev_b64 v[76:77], 12, v[76:77]
	v_cndmask_b32_e32 v73, v73, v103, vcc
	v_cndmask_b32_e32 v72, v72, v102, vcc
	v_lshl_add_u64 v[102:103], s[18:19], 0, v[74:75]
	v_lshl_add_u64 v[74:75], s[20:21], 0, v[74:75]
	v_lshl_add_u64 v[84:85], v[34:35], 0, v[84:85]
	v_lshl_add_u64 v[86:87], v[34:35], 0, v[86:87]
	v_lshlrev_b64 v[82:83], 12, v[82:83]
	v_lshlrev_b64 v[80:81], 12, v[80:81]
	v_lshl_add_u64 v[76:77], v[34:35], 0, v[76:77]
	v_lshl_add_u64 v[78:79], v[34:35], 0, v[78:79]
	v_lshl_add_u64 v[74:75], v[74:75], 0, s[58:59]
	v_cmp_gt_i32_e32 vcc, s75, v100
	global_load_dword v84, v[84:85], off
	s_nop 0
	global_load_dword v85, v[86:87], off
	v_lshlrev_b64 v[86:87], 12, v[90:91]
	v_lshlrev_b64 v[88:89], 12, v[88:89]
	global_load_dword v76, v[76:77], off
	s_nop 0
	global_load_dword v77, v[78:79], off
	v_lshl_add_u64 v[78:79], v[34:35], 0, v[80:81]
	v_lshl_add_u64 v[80:81], v[34:35], 0, v[82:83]
	v_cndmask_b32_e32 v74, v74, v102, vcc
	v_add_u32_e32 v102, s91, v46
	v_lshlrev_b64 v[90:91], 12, v[94:95]
	v_lshlrev_b64 v[92:93], 12, v[92:93]
	global_load_dword v78, v[78:79], off
	s_nop 0
	global_load_dword v79, v[80:81], off
	v_lshl_add_u64 v[80:81], v[34:35], 0, v[88:89]
; template <int MODE>
; __device__ __forceinline__ void transpose_item(const float* __restrict__ W, int K, int N, bf16_t* __restrict__ WT, LAS float* scr, int item, int lane, const float* __restrict__ ga, const float* __restrict__ gb) {
;     ...
;     for (int i = 0; i < 32; ++i) { const int kk = 2 * i + (lane >> 5); float v = W[(size_t)(k0 + kk) * N + n0 + (lane & 31)];
;         if (MODE == 1) { const int k = k0 + kk; v *= (k < 512) ? ga[k] : gb[k - 512]; }
;         scr[kk * 33 + (lane & 31)] = v; }
	v_lshl_add_u64 v[86:87], v[34:35], 0, v[86:87]
	v_cndmask_b32_e32 v75, v75, v103, vcc
	v_add_u32_e32 v104, s92, v47
	v_add_u32_e32 v106, s91, v48
	v_ashrrev_i32_e32 v103, 31, v102
	v_lshlrev_b64 v[94:95], 12, v[98:99]
	v_lshlrev_b64 v[96:97], 12, v[96:97]
	global_load_dword v82, v[80:81], off
	global_load_dword v83, v[86:87], off
	v_lshl_add_u64 v[80:81], v[34:35], 0, v[92:93]
	v_lshl_add_u64 v[86:87], v[34:35], 0, v[90:91]
	v_ashrrev_i32_e32 v107, 31, v106
	v_ashrrev_i32_e32 v105, 31, v104
	v_lshlrev_b64 v[98:99], 12, v[100:101]
	v_lshlrev_b64 v[100:101], 12, v[102:103]
	global_load_dword v80, v[80:81], off
	s_nop 0
	global_load_dword v81, v[86:87], off
	v_lshl_add_u64 v[86:87], v[34:35], 0, v[96:97]
	v_lshl_add_u64 v[88:89], v[34:35], 0, v[94:95]
	v_lshlrev_b64 v[126:127], 12, v[104:105]
	v_lshlrev_b64 v[90:91], 12, v[106:107]
	global_load_dword v86, v[86:87], off
	s_nop 0
	global_load_dword v87, v[88:89], off
	v_lshl_add_u64 v[88:89], v[34:35], 0, v[100:101]
	v_lshl_add_u64 v[92:93], v[34:35], 0, v[98:99]
	v_lshlrev_b64 v[124:125], 2, v[102:103]
	v_lshlrev_b64 v[94:95], 2, v[106:107]
	global_load_dword v88, v[88:89], off
	s_nop 0
	global_load_dword v89, v[92:93], off
	v_lshlrev_b64 v[98:99], 2, v[104:105]
	v_lshl_add_u64 v[90:91], v[34:35], 0, v[90:91]
	v_lshl_add_u64 v[92:93], v[34:35], 0, v[126:127]
	global_load_dword v90, v[90:91], off
	s_nop 0
	global_load_dword v91, v[92:93], off
	v_lshl_add_u64 v[92:93], s[18:19], 0, v[94:95]
	v_lshl_add_u64 v[94:95], s[20:21], 0, v[94:95]
	v_lshl_add_u64 v[96:97], s[18:19], 0, v[98:99]
	v_lshl_add_u64 v[98:99], s[20:21], 0, v[98:99]
	v_cmp_gt_i32_e64 s[12:13], s75, v104
	v_lshl_add_u64 v[104:105], s[20:21], 0, v[124:125]
	v_lshl_add_u64 v[94:95], v[94:95], 0, s[58:59]
	v_cmp_gt_i32_e32 vcc, s75, v106
	v_lshl_add_u64 v[98:99], v[98:99], 0, s[58:59]
	v_lshl_add_u64 v[100:101], s[18:19], 0, v[124:125]
	v_lshl_add_u64 v[104:105], v[104:105], 0, s[58:59]
	v_cmp_gt_i32_e64 s[14:15], s75, v102
	v_cndmask_b32_e64 v97, v99, v97, s[12:13]
	v_cndmask_b32_e64 v96, v98, v96, s[12:13]
	v_cndmask_b32_e64 v101, v105, v101, s[14:15]
	v_cndmask_b32_e64 v100, v104, v100, s[14:15]
	v_cndmask_b32_e32 v93, v95, v93, vcc
	v_cndmask_b32_e32 v92, v94, v92, vcc
	global_load_dword v52, v[52:53], off
	s_nop 0
	global_load_dword v53, v[50:51], off
	s_nop 0
	global_load_dword v50, v[56:57], off
	global_load_dword v51, v[54:55], off
	s_nop 0
	global_load_dword v54, v[60:61], off
	global_load_dword v55, v[58:59], off
	global_load_dword v56, v[64:65], off
	global_load_dword v57, v[62:63], off
	s_nop 0
	global_load_dword v58, v[68:69], off
	global_load_dword v59, v[66:67], off
	global_load_dword v60, v[72:73], off
	global_load_dword v61, v[70:71], off
	global_load_dword v62, v[100:101], off
	global_load_dword v63, v[74:75], off
	global_load_dword v64, v[92:93], off
	global_load_dword v65, v[96:97], off
	s_add_i32 s62, s62, 16
	s_add_i32 s61, s61, 16
	s_add_i32 s63, s63, -16
	v_add_u32_e32 v66, s91, v2
	v_add_u32_e32 v68, s92, v3
	v_add_u32_e32 v72, s92, v5
	v_add_u32_e32 v70, s91, v20
	v_add_u32_e32 v92, s92, v9
	v_add_u32_e32 v74, s91, v22
	v_add_u32_e32 v96, s92, v21
	v_add_u32_e32 v94, s91, v24
	v_add_u32_e32 v98, s92, v23
	v_add_u32_e32 v99, s91, v26
	v_add_u32_e32 v100, s92, v25
	v_add_u32_e32 v101, s91, v28
	v_add_u32_e32 v102, s92, v27
	v_add_u32_e32 v103, s91, v30
	v_add_u32_e32 v104, s92, v29
	v_add_u32_e32 v105, s91, v32
	s_cmp_lg_u32 s63, 0
	v_mad_u64_u32 v[66:67], s[12:13], v66, s1, v[8:9]
	v_mad_u64_u32 v[68:69], s[12:13], v68, s1, v[8:9]
	v_mad_u64_u32 v[70:71], s[12:13], v70, s1, v[8:9]
	v_mad_u64_u32 v[72:73], s[12:13], v72, s1, v[8:9]
	v_mad_u64_u32 v[74:75], s[12:13], v74, s1, v[8:9]
	v_mad_u64_u32 v[92:93], s[12:13], v92, s1, v[8:9]
	v_mad_u64_u32 v[94:95], s[12:13], v94, s1, v[8:9]
	v_mad_u64_u32 v[96:97], s[12:13], v96, s1, v[8:9]
	s_waitcnt vmcnt(14)
	v_pk_mul_f32 v[52:53], v[84:85], v[52:53]
	v_mad_u64_u32 v[84:85], s[12:13], v99, s1, v[8:9]
	v_mad_u64_u32 v[98:99], s[12:13], v98, s1, v[8:9]
	s_waitcnt vmcnt(12)
	v_pk_mul_f32 v[50:51], v[76:77], v[50:51]
	v_mad_u64_u32 v[76:77], s[12:13], v101, s1, v[8:9]
	v_mad_u64_u32 v[100:101], s[12:13], v100, s1, v[8:9]
	s_waitcnt vmcnt(10)
	v_pk_mul_f32 v[54:55], v[78:79], v[54:55]
	v_mad_u64_u32 v[78:79], s[12:13], v103, s1, v[8:9]
	v_mad_u64_u32 v[102:103], s[12:13], v102, s1, v[8:9]
	s_waitcnt vmcnt(8)
	v_pk_mul_f32 v[56:57], v[82:83], v[56:57]
	v_mad_u64_u32 v[82:83], s[12:13], v105, s1, v[8:9]
	v_mad_u64_u32 v[104:105], s[12:13], v104, s1, v[8:9]
	s_waitcnt vmcnt(6)
	v_pk_mul_f32 v[58:59], v[80:81], v[58:59]
	s_waitcnt vmcnt(4)
	v_pk_mul_f32 v[60:61], v[86:87], v[60:61]
	s_waitcnt vmcnt(2)
	v_pk_mul_f32 v[62:63], v[88:89], v[62:63]
	s_waitcnt vmcnt(0)
	v_pk_mul_f32 v[64:65], v[90:91], v[64:65]
	ds_write_b32 v66, v52
	ds_write_b32 v68, v53
	ds_write_b32 v70, v50
	ds_write_b32 v72, v51
	ds_write_b32 v74, v54
	ds_write_b32 v92, v55
	ds_write_b32 v94, v56
	ds_write_b32 v96, v57
	ds_write_b32 v84, v58
	ds_write_b32 v98, v59
	ds_write_b32 v76, v60
	ds_write_b32 v100, v61
	ds_write_b32 v78, v62
	ds_write_b32 v102, v63
	ds_write_b32 v82, v64
	ds_write_b32 v104, v65
	s_cbranch_scc1 .LBB0_92
; #define LAS __attribute__((address_space(3)))
; __device__ __forceinline__ unsigned cvtpk(float lo, float hi) { f32x2 v = {lo, hi}; bf16x2_t b = __builtin_convertvector(v, bf16x2_t); return __builtin_bit_cast(unsigned, b); }
; template <int MODE>
; __device__ __forceinline__ void transpose_item(const float* __restrict__ W, int K, int N, bf16_t* __restrict__ WT, LAS float* scr, int item, int lane, const float* __restrict__ ga, const float* __restrict__ gb) {
;     ...
;     asm volatile("s_waitcnt lgkmcnt(0)" ::: "memory");
;     const int c = lane & 7;
; #pragma unroll
;     for (int j = 0; j < 4; ++j) { const int n = (lane >> 3) + 8 * j; const LAS float* s = scr + (8 * c) * 33 + n;
;         u32x4 o; o.x = cvtpk(s[0 * 33], s[1 * 33]); o.y = cvtpk(s[2 * 33], s[3 * 33]); o.z = cvtpk(s[4 * 33], s[5 * 33]); o.w = cvtpk(s[6 * 33], s[7 * 33]);
;         const int nn = n0 + n; int drow = nn;
;         if (MODE == 2) drow = 256 * (nn >> 7) + (nn & 127);
;         if (MODE == 3) drow = 256 * (nn >> 7) + 128 + (nn & 127);
;         *(u32x4*)(WT + (size_t)drow * K + k0 + 8 * c) = o; }
;     asm volatile("s_waitcnt lgkmcnt(0)" ::: "memory");
	s_waitcnt lgkmcnt(0)
	ds_read2_b32 v[38:39], v110 offset0:33 offset1:41
	ds_read2_b32 v[40:41], v110 offset1:8
	ds_read2_b32 v[42:43], v110 offset0:66 offset1:74
	ds_read2_b32 v[44:45], v110 offset0:99 offset1:107
	ds_read2_b32 v[46:47], v110 offset0:132 offset1:140
	ds_read2_b32 v[50:51], v110 offset0:165 offset1:173
	ds_read2_b32 v[52:53], v110 offset0:198 offset1:206
	ds_read2_b32 v[54:55], v110 offset0:231 offset1:239
	v_add_u32_e32 v58, s60, v109
	s_lshl_b32 s34, s34, 1
	v_ashrrev_i32_e32 v59, 31, v58
	v_lshl_add_u64 v[56:57], v[14:15], 0, s[34:35]
	v_lshlrev_b64 v[58:59], 11, v[58:59]
	s_waitcnt lgkmcnt(6)
	v_cvt_pk_bf16_f32 v34, v40, v38
	s_waitcnt lgkmcnt(4)
	v_cvt_pk_bf16_f32 v35, v42, v44
	s_waitcnt lgkmcnt(2)
	v_cvt_pk_bf16_f32 v36, v46, v50
	s_waitcnt lgkmcnt(0)
	v_cvt_pk_bf16_f32 v37, v52, v54
	v_lshl_add_u64 v[58:59], v[56:57], 0, v[58:59]
	v_add_u32_e32 v38, s60, v111
	global_store_dwordx4 v[58:59], v[34:37], off sc1
	s_nop 1
	v_cvt_pk_bf16_f32 v34, v41, v39
	v_ashrrev_i32_e32 v39, 31, v38
	v_cvt_pk_bf16_f32 v35, v43, v45
	v_cvt_pk_bf16_f32 v36, v47, v51
	v_cvt_pk_bf16_f32 v37, v53, v55
	v_lshlrev_b64 v[38:39], 11, v[38:39]
	ds_read2_b32 v[40:41], v110 offset0:49 offset1:57
	ds_read2_b32 v[42:43], v110 offset0:16 offset1:24
	ds_read2_b32 v[44:45], v110 offset0:82 offset1:90
	ds_read2_b32 v[46:47], v110 offset0:115 offset1:123
	ds_read2_b32 v[50:51], v110 offset0:148 offset1:156
	ds_read2_b32 v[52:53], v110 offset0:181 offset1:189
	ds_read2_b32 v[54:55], v110 offset0:214 offset1:222
	ds_read2_b32 v[58:59], v110 offset0:247 offset1:255
	v_lshl_add_u64 v[38:39], v[56:57], 0, v[38:39]
	global_store_dwordx4 v[38:39], v[34:37], off sc1
	v_add_u32_e32 v38, s60, v112
	v_ashrrev_i32_e32 v39, 31, v38
	v_lshlrev_b64 v[38:39], 11, v[38:39]
	s_waitcnt lgkmcnt(6)
	v_cvt_pk_bf16_f32 v34, v42, v40
	s_waitcnt lgkmcnt(4)
	v_cvt_pk_bf16_f32 v35, v44, v46
	s_waitcnt lgkmcnt(2)
	v_cvt_pk_bf16_f32 v36, v50, v52
	s_waitcnt lgkmcnt(0)
	v_cvt_pk_bf16_f32 v37, v54, v58
	v_lshl_add_u64 v[38:39], v[56:57], 0, v[38:39]
	global_store_dwordx4 v[38:39], v[34:37], off sc1
	v_add_u32_e32 v38, s60, v113
	v_ashrrev_i32_e32 v39, 31, v38
	v_lshlrev_b64 v[38:39], 11, v[38:39]
	v_cvt_pk_bf16_f32 v34, v43, v41
	v_cvt_pk_bf16_f32 v35, v45, v47
	v_cvt_pk_bf16_f32 v36, v51, v53
	v_cvt_pk_bf16_f32 v37, v55, v59
	v_lshl_add_u64 v[38:39], v[56:57], 0, v[38:39]
	global_store_dwordx4 v[38:39], v[34:37], off sc1
	s_waitcnt lgkmcnt(0)

; #define LAS __attribute__((address_space(3)))
; __device__ __forceinline__ unsigned cvtpk(float lo, float hi) { f32x2 v = {lo, hi}; bf16x2_t b = __builtin_convertvector(v, bf16x2_t); return __builtin_bit_cast(unsigned, b); }
; template <int MODE>
; __device__ __forceinline__ void transpose_item(const float* __restrict__ W, int K, int N, bf16_t* __restrict__ WT, LAS float* scr, int item, int lane, const float* __restrict__ ga, const float* __restrict__ gb) {
;     const int nblk = N / 32, kb = item / nblk, nb = item % nblk, k0 = 64 * kb, n0 = 32 * nb;
; #pragma unroll 8
;     for (int i = 0; i < 32; ++i) { const int kk = 2 * i + (lane >> 5); float v = W[(size_t)(k0 + kk) * N + n0 + (lane & 31)];
;         if (MODE == 1) { const int k = k0 + kk; v *= (k < 512) ? ga[k] : gb[k - 512]; }
;         scr[kk * 33 + (lane & 31)] = v; }
;     asm volatile("s_waitcnt lgkmcnt(0)" ::: "memory");
;     const int c = lane & 7;
; #pragma unroll
;     for (int j = 0; j < 4; ++j) { const int n = (lane >> 3) + 8 * j; const LAS float* s = scr + (8 * c) * 33 + n;
;         u32x4 o; o.x = cvtpk(s[0 * 33], s[1 * 33]); o.y = cvtpk(s[2 * 33], s[3 * 33]); o.z = cvtpk(s[4 * 33], s[5 * 33]); o.w = cvtpk(s[6 * 33], s[7 * 33]);
;         const int nn = n0 + n; int drow = nn;
;         if (MODE == 2) drow = 256 * (nn >> 7) + (nn & 127);
;         if (MODE == 3) drow = 256 * (nn >> 7) + 128 + (nn & 127);
;         *(u32x4*)(WT + (size_t)drow * K + k0 + 8 * c) = o; }
;     asm volatile("s_waitcnt lgkmcnt(0)" ::: "memory");
.LBB0_97:
	s_lshl_b32 s19, s15, 1
	s_lshl_b32 s34, s14, 1
	v_add_u32_e32 v50, s19, v6
	v_add_u32_e32 v52, s34, v31
	v_add_u32_e32 v56, s34, v33
	v_add_u32_e32 v54, s19, v36
	v_add_u32_e32 v60, s34, v37
	v_add_u32_e32 v58, s19, v38
	v_add_u32_e32 v64, s34, v39
	v_add_u32_e32 v62, s19, v40
	v_add_u32_e32 v68, s34, v41
	v_add_u32_e32 v66, s19, v42
	v_add_u32_e32 v72, s34, v43
	v_add_u32_e32 v70, s19, v44
	v_add_u32_e32 v76, s34, v45
	v_add_u32_e32 v74, s19, v46
	v_add_u32_e32 v80, s34, v47
	v_add_u32_e32 v78, s19, v48
	v_mad_i64_i32 v[50:51], s[20:21], v50, s76, v[34:35]
	v_mad_i64_i32 v[52:53], s[20:21], v52, s76, v[34:35]
	v_mad_i64_i32 v[54:55], s[20:21], v54, s76, v[34:35]
	v_mad_i64_i32 v[56:57], s[20:21], v56, s76, v[34:35]
	v_mad_i64_i32 v[58:59], s[20:21], v58, s76, v[34:35]
	v_mad_i64_i32 v[60:61], s[20:21], v60, s76, v[34:35]
	v_mad_i64_i32 v[62:63], s[20:21], v62, s76, v[34:35]
	v_mad_i64_i32 v[64:65], s[20:21], v64, s76, v[34:35]
	v_mad_i64_i32 v[66:67], s[20:21], v66, s76, v[34:35]
	v_mad_i64_i32 v[68:69], s[20:21], v68, s76, v[34:35]
	v_mad_i64_i32 v[70:71], s[20:21], v70, s76, v[34:35]
	v_mad_i64_i32 v[72:73], s[20:21], v72, s76, v[34:35]
	v_mad_i64_i32 v[74:75], s[20:21], v74, s76, v[34:35]
	v_mad_i64_i32 v[76:77], s[20:21], v76, s76, v[34:35]
	v_mad_i64_i32 v[78:79], s[20:21], v78, s76, v[34:35]
	v_mad_i64_i32 v[80:81], s[20:21], v80, s76, v[34:35]
	global_load_dword v82, v[50:51], off
	global_load_dword v83, v[52:53], off
	global_load_dword v84, v[54:55], off
	global_load_dword v85, v[56:57], off
	global_load_dword v86, v[58:59], off
	global_load_dword v87, v[60:61], off
	global_load_dword v88, v[62:63], off
	global_load_dword v89, v[64:65], off
	global_load_dword v90, v[66:67], off
	global_load_dword v91, v[68:69], off
	global_load_dword v92, v[70:71], off
	global_load_dword v93, v[72:73], off
	global_load_dword v94, v[74:75], off
	global_load_dword v95, v[76:77], off
	global_load_dword v96, v[78:79], off
	global_load_dword v97, v[80:81], off
	s_add_i32 s15, s15, 16
	s_add_i32 s14, s14, 16
	s_add_i32 s18, s18, -16
	v_add_u32_e32 v50, s19, v2
	v_add_u32_e32 v52, s34, v3
	v_add_u32_e32 v56, s34, v5
	v_add_u32_e32 v54, s19, v20
	v_add_u32_e32 v60, s34, v9
	v_add_u32_e32 v58, s19, v22
	v_add_u32_e32 v64, s34, v21
	v_add_u32_e32 v62, s19, v24
	v_add_u32_e32 v68, s34, v23
	v_add_u32_e32 v66, s19, v26
	v_add_u32_e32 v72, s34, v25
	v_add_u32_e32 v70, s19, v28
	v_add_u32_e32 v76, s34, v27
	v_add_u32_e32 v74, s19, v30
	v_add_u32_e32 v80, s34, v29
	v_add_u32_e32 v78, s19, v32
	s_cmp_lg_u32 s18, 0
	v_mad_u64_u32 v[50:51], s[20:21], v50, s1, v[8:9]
	v_mad_u64_u32 v[52:53], s[20:21], v52, s1, v[8:9]
	v_mad_u64_u32 v[54:55], s[20:21], v54, s1, v[8:9]
	v_mad_u64_u32 v[56:57], s[20:21], v56, s1, v[8:9]
	v_mad_u64_u32 v[58:59], s[20:21], v58, s1, v[8:9]
	v_mad_u64_u32 v[60:61], s[20:21], v60, s1, v[8:9]
	v_mad_u64_u32 v[62:63], s[20:21], v62, s1, v[8:9]
	v_mad_u64_u32 v[64:65], s[20:21], v64, s1, v[8:9]
	v_mad_u64_u32 v[66:67], s[20:21], v66, s1, v[8:9]
	v_mad_u64_u32 v[68:69], s[20:21], v68, s1, v[8:9]
	v_mad_u64_u32 v[70:71], s[20:21], v70, s1, v[8:9]
	v_mad_u64_u32 v[72:73], s[20:21], v72, s1, v[8:9]
	v_mad_u64_u32 v[74:75], s[20:21], v74, s1, v[8:9]
	v_mad_u64_u32 v[76:77], s[20:21], v76, s1, v[8:9]
	v_mad_u64_u32 v[78:79], s[20:21], v78, s1, v[8:9]
	v_mad_u64_u32 v[80:81], s[20:21], v80, s1, v[8:9]
	s_waitcnt vmcnt(15)
	ds_write_b32 v50, v82
	s_waitcnt vmcnt(14)
	ds_write_b32 v52, v83
	s_waitcnt vmcnt(13)
	ds_write_b32 v54, v84
	s_waitcnt vmcnt(12)
	ds_write_b32 v56, v85
	s_waitcnt vmcnt(11)
	ds_write_b32 v58, v86
	s_waitcnt vmcnt(10)
	ds_write_b32 v60, v87
	s_waitcnt vmcnt(9)
	ds_write_b32 v62, v88
	s_waitcnt vmcnt(8)
	ds_write_b32 v64, v89
	s_waitcnt vmcnt(7)
	ds_write_b32 v66, v90
	s_waitcnt vmcnt(6)
	ds_write_b32 v68, v91
	s_waitcnt vmcnt(5)
	ds_write_b32 v70, v92
	s_waitcnt vmcnt(4)
	ds_write_b32 v72, v93
	s_waitcnt vmcnt(3)
	ds_write_b32 v74, v94
	s_waitcnt vmcnt(2)
	ds_write_b32 v76, v95
	s_waitcnt vmcnt(1)
	ds_write_b32 v78, v96
	s_waitcnt vmcnt(0)
	ds_write_b32 v80, v97
	s_cbranch_scc1 .LBB0_97
	s_waitcnt lgkmcnt(0)
	ds_read2_b32 v[38:39], v110 offset0:33 offset1:41
	ds_read2_b32 v[40:41], v110 offset1:8
	ds_read2_b32 v[42:43], v110 offset0:66 offset1:74
	ds_read2_b32 v[44:45], v110 offset0:99 offset1:107
	ds_read2_b32 v[46:47], v110 offset0:132 offset1:140
	ds_read2_b32 v[50:51], v110 offset0:165 offset1:173
	ds_read2_b32 v[52:53], v110 offset0:198 offset1:206
	ds_read2_b32 v[54:55], v110 offset0:231 offset1:239
	s_and_b32 s13, 0xffff, s13
	s_and_b32 s12, 0xffff, s12
	v_add_u32_e32 v58, s13, v109
	s_lshl_b32 s34, s12, 1
	v_ashrrev_i32_e32 v59, 31, v58
	v_lshl_add_u64 v[56:57], v[16:17], 0, s[34:35]
	v_lshlrev_b64 v[58:59], 11, v[58:59]
	s_waitcnt lgkmcnt(6)
	v_cvt_pk_bf16_f32 v34, v40, v38
	s_waitcnt lgkmcnt(4)
	v_cvt_pk_bf16_f32 v35, v42, v44
	s_waitcnt lgkmcnt(2)
	v_cvt_pk_bf16_f32 v36, v46, v50
	s_waitcnt lgkmcnt(0)
	v_cvt_pk_bf16_f32 v37, v52, v54
	v_lshl_add_u64 v[58:59], v[56:57], 0, v[58:59]
	v_add_u32_e32 v38, s13, v111
	global_store_dwordx4 v[58:59], v[34:37], off sc1
	s_nop 1
	v_cvt_pk_bf16_f32 v34, v41, v39
	v_ashrrev_i32_e32 v39, 31, v38
	v_cvt_pk_bf16_f32 v35, v43, v45
	v_cvt_pk_bf16_f32 v36, v47, v51
	v_cvt_pk_bf16_f32 v37, v53, v55
	v_lshlrev_b64 v[38:39], 11, v[38:39]
	ds_read2_b32 v[40:41], v110 offset0:49 offset1:57
	ds_read2_b32 v[42:43], v110 offset0:16 offset1:24
	ds_read2_b32 v[44:45], v110 offset0:82 offset1:90
	ds_read2_b32 v[46:47], v110 offset0:115 offset1:123
	ds_read2_b32 v[50:51], v110 offset0:148 offset1:156
	ds_read2_b32 v[52:53], v110 offset0:181 offset1:189
	ds_read2_b32 v[54:55], v110 offset0:214 offset1:222
	ds_read2_b32 v[58:59], v110 offset0:247 offset1:255
	v_lshl_add_u64 v[38:39], v[56:57], 0, v[38:39]
	global_store_dwordx4 v[38:39], v[34:37], off sc1
	v_add_u32_e32 v38, s13, v112
	v_ashrrev_i32_e32 v39, 31, v38
	v_lshlrev_b64 v[38:39], 11, v[38:39]
	s_waitcnt lgkmcnt(6)
	v_cvt_pk_bf16_f32 v34, v42, v40
	s_waitcnt lgkmcnt(4)
	v_cvt_pk_bf16_f32 v35, v44, v46
	s_waitcnt lgkmcnt(2)
	v_cvt_pk_bf16_f32 v36, v50, v52
	s_waitcnt lgkmcnt(0)
	v_cvt_pk_bf16_f32 v37, v54, v58
	v_lshl_add_u64 v[38:39], v[56:57], 0, v[38:39]
	global_store_dwordx4 v[38:39], v[34:37], off sc1
	v_add_u32_e32 v38, s13, v113
	v_ashrrev_i32_e32 v39, 31, v38
	v_lshlrev_b64 v[38:39], 11, v[38:39]
	v_cvt_pk_bf16_f32 v34, v43, v41
	v_cvt_pk_bf16_f32 v35, v45, v47
	v_cvt_pk_bf16_f32 v36, v51, v53
	v_cvt_pk_bf16_f32 v37, v55, v59
	v_lshl_add_u64 v[38:39], v[56:57], 0, v[38:39]
	global_store_dwordx4 v[38:39], v[34:37], off sc1
	s_waitcnt lgkmcnt(0)
